# t1 + prep row loop: rope-table and 16-bit key loads issued with the row loads, one vmcnt wait per row instead of three
# baseline (speedup 1.0000x reference)
.LBB0_330:
	v_lshl_add_u64 v[40:41], s[10:11], 0, v[26:27]
	v_add_co_u32_e32 v0, vcc, 0x19400000, v40
	v_lshl_add_u64 v[30:31], s[10:11], 0, v[22:23]
	s_nop 0
	v_addc_co_u32_e32 v1, vcc, 0, v41, vcc
	v_add_co_u32_e32 v2, vcc, 0x19401000, v40
	v_lshl_add_u64 v[38:39], s[10:11], 0, v[28:29]
	s_nop 0
	v_addc_co_u32_e32 v3, vcc, 0, v41, vcc
	v_add_co_u32_e32 v30, vcc, 0x19401000, v30
	s_mov_b64 s[8:9], 0x19401800
	s_nop 0
	v_addc_co_u32_e32 v31, vcc, 0, v31, vcc
	global_load_dword v52, v[2:3], off offset:2176
	global_load_dword v50, v[2:3], off offset:2688
	global_load_dword v48, v[2:3], off offset:3200
	global_load_dword v47, v[30:31], off offset:1024
	global_load_dword v46, v[30:31], off offset:1280
	global_load_dword v45, v[30:31], off offset:1536
	global_load_dword v44, v[30:31], off offset:1792
	global_load_dword v54, v[2:3], off
	global_load_dword v59, v[0:1], off offset:3072
	global_load_dword v58, v[0:1], off offset:3136
	global_load_dword v53, v[38:39], off
	global_load_dword v57, v[0:1], off offset:3584
	global_load_dword v56, v[0:1], off offset:3648
	global_load_dword v51, v[38:39], off offset:512
	global_load_dword v49, v[38:39], off offset:1024
	global_load_dword v55, v[38:39], off offset:-2176
	v_lshl_add_u64 v[30:31], s[10:11], 0, v[24:25]
	v_lshl_add_u64 v[32:33], v[30:31], 0, s[8:9]
	v_mov_b32_e32 v37, 0
	v_mov_b32_e32 v34, 0
	v_mov_b32_e32 v35, 0
	s_cmpk_lt_i32 s18, 0x4000
	v_mov_b32_e32 v36, 1.0
	s_cselect_b64 s[16:17], -1, 0
	s_cmpk_gt_i32 s18, 0x3fff
	v_mov_b32_e32 v2, 1.0
	v_mov_b32_e32 v3, 0
	v_mov_b32_e32 v0, 1.0
	v_mov_b32_e32 v1, 0
	s_cbranch_scc1 .Lprep_notab
	s_lshr_b32 s8, s18, 6
	v_mov_b32_e32 v0, s18
	v_mov_b32_e32 v1, s8
	v_cndmask_b32_e64 v0, v0, v1, s[6:7]
	v_and_b32_e32 v0, 63, v0
	v_lshlrev_b32_e32 v1, 3, v42
	v_lshlrev_b32_e32 v2, 3, v43
	v_lshl_or_b32 v1, v0, 8, v1
	v_lshl_or_b32 v36, v0, 7, v2
	global_load_dwordx4 v[0:3], v1, s[12:13]
	s_nop 0
	global_load_dwordx2 v[36:37], v36, s[14:15]
.Lprep_notab:
	s_and_saveexec_b64 s[8:9], s[4:5]
	s_cbranch_execz .LBB0_332
	v_add_co_u32_e32 v60, vcc, 0x19401000, v30
	s_nop 1
	v_addc_co_u32_e32 v61, vcc, 0, v31, vcc
	global_load_ushort v34, v[60:61], off offset:2080
	s_nop 0
	global_load_ushort v35, v[32:33], off

.LBB0_334:
	s_andn2_b64 vcc, exec, s[16:17]
	s_cbranch_vccnz .Lprep_ctx
	s_waitcnt vmcnt(0)
	v_lshlrev_b32_e32 v34, 16, v34
	v_lshlrev_b32_e32 v35, 16, v35
	v_lshlrev_b32_e32 v71, 16, v58
	v_lshlrev_b32_e32 v70, 16, v59
	v_and_b32_e32 v58, 0xffff0000, v58
	v_mul_f32_e32 v72, v1, v71
	v_and_b32_e32 v59, 0xffff0000, v59
	v_fma_f32 v72, v0, v70, -v72
	v_mul_f32_e32 v73, v3, v58
	v_fma_f32 v73, v2, v59, -v73
	v_bfe_u32 v74, v72, 16, 1
	v_add3_u32 v72, v72, v74, s69
	v_bfe_u32 v74, v73, 16, 1
	s_mov_b64 s[8:9], 0x19400c00
	v_lshrrev_b32_e32 v72, 16, v72
	v_add3_u32 v73, v73, v74, s69
	v_lshl_add_u64 v[60:61], v[40:41], 0, s[8:9]
	v_and_or_b32 v72, v73, s19, v72
	global_store_dword v[60:61], v72, off
	v_mul_f32_e32 v60, v0, v71
	v_fmac_f32_e32 v60, v1, v70
	v_mul_f32_e32 v58, v2, v58
	v_fmac_f32_e32 v58, v3, v59
	v_bfe_u32 v59, v60, 16, 1
	v_add3_u32 v59, v60, v59, s69
	v_bfe_u32 v60, v58, 16, 1
	s_mov_b64 s[8:9], 0x19400c40
	v_lshrrev_b32_e32 v59, 16, v59
	v_add3_u32 v58, v58, v60, s69
	v_lshl_add_u64 v[62:63], v[40:41], 0, s[8:9]
	v_and_or_b32 v58, v58, s19, v59
	v_lshlrev_b32_e32 v59, 16, v56
	global_store_dword v[62:63], v58, off
	v_lshlrev_b32_e32 v58, 16, v57
	v_and_b32_e32 v56, 0xffff0000, v56
	v_mul_f32_e32 v60, v1, v59
	v_mul_f32_e32 v59, v0, v59
	v_and_b32_e32 v57, 0xffff0000, v57
	v_mul_f32_e32 v61, v3, v56
	v_fmac_f32_e32 v59, v1, v58
	v_mul_f32_e32 v56, v2, v56
	v_fma_f32 v61, v2, v57, -v61
	v_fmac_f32_e32 v56, v3, v57
	v_bfe_u32 v57, v59, 16, 1
	s_mov_b64 s[8:9], 0x19400e00
	v_fma_f32 v60, v0, v58, -v60
	v_add3_u32 v57, v59, v57, s69
	v_bfe_u32 v58, v56, 16, 1
	v_lshl_add_u64 v[64:65], v[40:41], 0, s[8:9]
	s_mov_b64 s[8:9], 0x19400e40
	v_bfe_u32 v62, v60, 16, 1
	v_lshrrev_b32_e32 v57, 16, v57
	v_add3_u32 v56, v56, v58, s69
	v_lshl_add_u64 v[66:67], v[40:41], 0, s[8:9]
	v_add3_u32 v60, v60, v62, s69
	v_bfe_u32 v62, v61, 16, 1
	v_and_or_b32 v56, v56, s19, v57
	v_lshlrev_b32_e32 v57, 16, v55
	v_lshrrev_b32_e32 v60, 16, v60
	v_add3_u32 v61, v61, v62, s69
	global_store_dword v[66:67], v56, off
	v_lshlrev_b32_e32 v56, 16, v54
	v_and_b32_e32 v55, 0xffff0000, v55
	v_mul_f32_e32 v58, v1, v57
	v_mul_f32_e32 v57, v0, v57
	v_and_or_b32 v60, v61, s19, v60
	v_and_b32_e32 v54, 0xffff0000, v54
	v_fma_f32 v58, v0, v56, -v58
	v_mul_f32_e32 v59, v3, v55
	v_fmac_f32_e32 v57, v1, v56
	v_mul_f32_e32 v55, v2, v55
	global_store_dword v[64:65], v60, off
	v_fma_f32 v59, v2, v54, -v59
	v_bfe_u32 v60, v58, 16, 1
	v_fmac_f32_e32 v55, v3, v54
	v_bfe_u32 v54, v57, 16, 1
	v_add3_u32 v58, v58, v60, s69
	v_bfe_u32 v60, v59, 16, 1
	v_add3_u32 v54, v57, v54, s69
	v_bfe_u32 v56, v55, 16, 1
	s_mov_b64 s[8:9], 0x19401000
	v_lshrrev_b32_e32 v58, 16, v58
	v_add3_u32 v59, v59, v60, s69
	v_lshrrev_b32_e32 v54, 16, v54
	v_add3_u32 v55, v55, v56, s69
	v_lshl_add_u64 v[68:69], v[40:41], 0, s[8:9]
	v_and_or_b32 v58, v59, s19, v58
	v_and_or_b32 v54, v55, s19, v54
	global_store_dword v[68:69], v58, off
	global_store_dword v[38:39], v54, off offset:-2176
	s_branch .LBB0_336
.Lprep_ctx:
	s_waitcnt vmcnt(0)
	v_lshlrev_b32_e32 v34, 16, v34
	v_lshlrev_b32_e32 v35, 16, v35
.LBB0_336:
	v_and_b32_e32 v57, 0xffff0000, v52
	v_and_b32_e32 v59, 0xffff0000, v53
	v_lshlrev_b32_e32 v56, 16, v52
	v_lshlrev_b32_e32 v58, 16, v53
	v_mul_f32_e32 v52, v57, v57
	v_mul_f32_e32 v53, v59, v59
	v_fmac_f32_e32 v52, v56, v56
	v_fmac_f32_e32 v53, v58, v58
	v_add_f32_e32 v52, v52, v53
	s_nop 1
	v_add_f32_dpp v52, v52, v52 quad_perm:[1,0,3,2] row_mask:0xf bank_mask:0xf
	s_nop 1
	v_add_f32_dpp v52, v52, v52 quad_perm:[2,3,0,1] row_mask:0xf bank_mask:0xf
	s_nop 1
	v_add_f32_dpp v52, v52, v52 row_half_mirror row_mask:0xf bank_mask:0xf
	s_nop 1
	v_add_f32_dpp v52, v52, v52 row_ror:8 row_mask:0xf bank_mask:0xf
	s_and_b64 s[16:17], s[4:5], s[16:17]
	v_readlane_b32 s9, v52, 16
	v_readlane_b32 s8, v52, 0
	s_nop 0
	v_mov_b32_e32 v53, s9
	v_readlane_b32 s9, v52, 48
	v_add_f32_e32 v53, s8, v53
	v_readlane_b32 s8, v52, 32
	v_mov_b32_e32 v52, s9
	s_nop 0
	v_add_f32_e32 v52, s8, v52
	v_cndmask_b32_e64 v52, v52, v53, s[4:5]
	v_fmamk_f32 v52, v52, 0x3c000000, v229
	v_mul_f32_e32 v53, 0x4f800000, v52
	v_cmp_gt_f32_e32 vcc, s24, v52
	s_nop 1
	v_cndmask_b32_e32 v52, v52, v53, vcc
	v_sqrt_f32_e32 v53, v52
	s_nop 0
	v_add_u32_e32 v54, -1, v53
	v_fma_f32 v55, -v54, v53, v52
	v_cmp_ge_f32_e64 s[8:9], 0, v55
	v_add_u32_e32 v55, 1, v53
	s_nop 0
	v_cndmask_b32_e64 v54, v53, v54, s[8:9]
	v_fma_f32 v53, -v55, v53, v52
	v_cmp_lt_f32_e64 s[8:9], 0, v53
	s_nop 1
	v_cndmask_b32_e64 v53, v54, v55, s[8:9]
	v_mul_f32_e32 v54, 0x37800000, v53
	v_cndmask_b32_e32 v53, v53, v54, vcc
	v_cmp_class_f32_e32 vcc, v52, v230
	s_nop 1
	v_cndmask_b32_e32 v60, v53, v52, vcc
	v_div_scale_f32 v61, s[8:9], v60, v60, 1.0
	v_rcp_f32_e32 v62, v61
	s_mov_b64 s[8:9], 0x19401880
	v_lshl_add_u64 v[52:53], v[40:41], 0, s[8:9]
	s_mov_b64 s[8:9], 0x19401a80
	v_fma_f32 v63, -v61, v62, 1.0
	v_fmac_f32_e32 v62, v63, v62
	v_div_scale_f32 v63, vcc, 1.0, v60, 1.0
	v_mul_f32_e32 v64, v63, v62
	v_fma_f32 v65, -v61, v64, v63
	v_fmac_f32_e32 v64, v65, v62
	v_fma_f32 v61, -v61, v64, v63
	v_div_fmas_f32 v61, v61, v62, v64
	v_div_fixup_f32 v60, v61, v60, 1.0
	v_mul_f32_e32 v61, v4, v60
	v_mul_f32_e32 v56, v61, v56
	v_mul_f32_e32 v61, v5, v60
	v_mul_f32_e32 v57, v61, v57
	v_mul_f32_e32 v61, v6, v60
	v_mul_f32_e32 v58, v61, v58
	v_mul_f32_e32 v60, v7, v60
	v_mul_f32_e32 v59, v60, v59
	v_mul_f32_e32 v60, v1, v58
	v_fma_f32 v60, v0, v56, -v60
	v_mul_f32_e32 v61, v3, v59
	v_fma_f32 v61, v2, v57, -v61
	v_bfe_u32 v62, v60, 16, 1
	v_add3_u32 v60, v60, v62, s69
	v_bfe_u32 v62, v61, 16, 1
	v_lshrrev_b32_e32 v60, 16, v60
	v_add3_u32 v61, v61, v62, s69
	v_and_or_b32 v60, v61, s19, v60
	global_store_dword v[52:53], v60, off
	v_mul_f32_e32 v52, v1, v56
	v_fmac_f32_e32 v52, v0, v58
	v_mul_f32_e32 v53, v3, v57
	v_lshlrev_b32_e32 v57, 16, v50
	v_and_b32_e32 v50, 0xffff0000, v50
	v_lshlrev_b32_e32 v58, 16, v51
	v_and_b32_e32 v51, 0xffff0000, v51
	v_fmac_f32_e32 v53, v2, v59
	v_mul_f32_e32 v59, v50, v50
	v_mul_f32_e32 v60, v51, v51
	v_fmac_f32_e32 v59, v57, v57
	v_fmac_f32_e32 v60, v58, v58
	v_lshl_add_u64 v[54:55], v[40:41], 0, s[8:9]
	s_mov_b64 s[8:9], 0x19401c80
	v_add_f32_e32 v59, v59, v60
	v_lshl_add_u64 v[40:41], v[40:41], 0, s[8:9]
	s_nop 1
	v_add_f32_dpp v59, v59, v59 quad_perm:[1,0,3,2] row_mask:0xf bank_mask:0xf
	s_nop 1
	v_add_f32_dpp v59, v59, v59 quad_perm:[2,3,0,1] row_mask:0xf bank_mask:0xf
	s_nop 1
	v_add_f32_dpp v59, v59, v59 row_half_mirror row_mask:0xf bank_mask:0xf
	s_nop 1
	v_add_f32_dpp v59, v59, v59 row_ror:8 row_mask:0xf bank_mask:0xf
	v_bfe_u32 v56, v52, 16, 1
	v_readlane_b32 s9, v59, 16
	v_readlane_b32 s8, v59, 0
	v_add3_u32 v52, v52, v56, s69
	v_mov_b32_e32 v60, s9
	v_readlane_b32 s9, v59, 48
	v_add_f32_e32 v60, s8, v60
	v_readlane_b32 s8, v59, 32
	v_mov_b32_e32 v59, s9
	v_bfe_u32 v56, v53, 16, 1
	v_add_f32_e32 v59, s8, v59
	v_cndmask_b32_e64 v59, v59, v60, s[4:5]
	v_fmamk_f32 v59, v59, 0x3c000000, v229
	v_mul_f32_e32 v60, 0x4f800000, v59
	v_cmp_gt_f32_e32 vcc, s24, v59
	v_lshrrev_b32_e32 v52, 16, v52
	v_add3_u32 v53, v53, v56, s69
	v_cndmask_b32_e32 v59, v59, v60, vcc
	v_sqrt_f32_e32 v60, v59
	v_and_or_b32 v52, v53, s19, v52
	global_store_dword v[38:39], v52, off
	v_add_u32_e32 v61, -1, v60
	v_fma_f32 v62, -v61, v60, v59
	v_cmp_ge_f32_e64 s[8:9], 0, v62
	v_add_u32_e32 v62, 1, v60
	s_nop 0
	v_cndmask_b32_e64 v61, v60, v61, s[8:9]
	v_fma_f32 v60, -v62, v60, v59
	v_cmp_lt_f32_e64 s[8:9], 0, v60
	s_nop 1
	v_cndmask_b32_e64 v60, v61, v62, s[8:9]
	v_mul_f32_e32 v61, 0x37800000, v60
	v_cndmask_b32_e32 v60, v60, v61, vcc
	v_cmp_class_f32_e32 vcc, v59, v230
	s_nop 1
	v_cndmask_b32_e32 v59, v60, v59, vcc
	v_div_scale_f32 v60, s[8:9], v59, v59, 1.0
	v_rcp_f32_e32 v61, v60
	s_nop 0
	v_fma_f32 v52, -v60, v61, 1.0
	v_fmac_f32_e32 v61, v52, v61
	v_div_scale_f32 v52, vcc, 1.0, v59, 1.0
	v_mul_f32_e32 v53, v52, v61
	v_fma_f32 v56, -v60, v53, v52
	v_fmac_f32_e32 v53, v56, v61
	v_fma_f32 v52, -v60, v53, v52
	v_div_fmas_f32 v52, v52, v61, v53
	v_div_fixup_f32 v52, v52, v59, 1.0
	v_mul_f32_e32 v56, v5, v52
	v_mul_f32_e32 v50, v56, v50
	v_mul_f32_e32 v56, v6, v52
	v_mul_f32_e32 v53, v4, v52
	v_mul_f32_e32 v56, v56, v58
	v_mul_f32_e32 v52, v7, v52
	v_mul_f32_e32 v53, v53, v57
	v_mul_f32_e32 v51, v52, v51
	v_mul_f32_e32 v52, v1, v56
	v_fma_f32 v52, v0, v53, -v52
	v_mul_f32_e32 v57, v3, v51
	v_fma_f32 v57, v2, v50, -v57
	v_bfe_u32 v58, v52, 16, 1
	v_add3_u32 v52, v52, v58, s69
	v_bfe_u32 v58, v57, 16, 1
	v_lshrrev_b32_e32 v52, 16, v52
	v_add3_u32 v57, v57, v58, s69
	v_and_or_b32 v52, v57, s19, v52
	global_store_dword v[54:55], v52, off
	v_mul_f32_e32 v52, v1, v53
	v_lshlrev_b32_e32 v53, 16, v48
	v_and_b32_e32 v48, 0xffff0000, v48
	v_lshlrev_b32_e32 v54, 16, v49
	v_and_b32_e32 v49, 0xffff0000, v49
	v_fmac_f32_e32 v52, v0, v56
	v_mul_f32_e32 v55, v48, v48
	v_mul_f32_e32 v56, v49, v49
	v_fmac_f32_e32 v55, v53, v53
	v_fmac_f32_e32 v56, v54, v54
	v_add_f32_e32 v55, v55, v56
	s_nop 1
	v_add_f32_dpp v55, v55, v55 quad_perm:[1,0,3,2] row_mask:0xf bank_mask:0xf
	s_nop 1
	v_add_f32_dpp v55, v55, v55 quad_perm:[2,3,0,1] row_mask:0xf bank_mask:0xf
	s_nop 1
	v_add_f32_dpp v55, v55, v55 row_half_mirror row_mask:0xf bank_mask:0xf
	s_nop 1
	v_add_f32_dpp v55, v55, v55 row_ror:8 row_mask:0xf bank_mask:0xf
	v_mul_f32_e32 v50, v3, v50
	v_readlane_b32 s9, v55, 16
	v_readlane_b32 s8, v55, 0
	v_fmac_f32_e32 v50, v2, v51
	v_mov_b32_e32 v56, s9
	v_readlane_b32 s9, v55, 48
	v_add_f32_e32 v56, s8, v56
	v_readlane_b32 s8, v55, 32
	v_mov_b32_e32 v55, s9
	v_bfe_u32 v51, v52, 16, 1
	v_add_f32_e32 v55, s8, v55
	v_cndmask_b32_e64 v55, v55, v56, s[4:5]
	v_fmamk_f32 v55, v55, 0x3c000000, v229
	v_mul_f32_e32 v56, 0x4f800000, v55
	v_cmp_gt_f32_e32 vcc, s24, v55
	v_add3_u32 v51, v52, v51, s69
	v_bfe_u32 v52, v50, 16, 1
	v_cndmask_b32_e32 v55, v55, v56, vcc
	v_sqrt_f32_e32 v56, v55
	v_lshrrev_b32_e32 v51, 16, v51
	v_add3_u32 v50, v50, v52, s69
	v_and_or_b32 v50, v50, s19, v51
	v_add_u32_e32 v57, -1, v56
	v_fma_f32 v58, -v57, v56, v55
	v_cmp_ge_f32_e64 s[8:9], 0, v58
	v_add_u32_e32 v58, 1, v56
	global_store_dword v[38:39], v50, off offset:512
	v_cndmask_b32_e64 v57, v56, v57, s[8:9]
	v_fma_f32 v56, -v58, v56, v55
	v_cmp_lt_f32_e64 s[8:9], 0, v56
	s_nop 1
	v_cndmask_b32_e64 v56, v57, v58, s[8:9]
	v_mul_f32_e32 v57, 0x37800000, v56
	v_cndmask_b32_e32 v56, v56, v57, vcc
	v_cmp_class_f32_e32 vcc, v55, v230
	s_nop 1
	v_cndmask_b32_e32 v55, v56, v55, vcc
	v_div_scale_f32 v56, s[8:9], v55, v55, 1.0
	v_rcp_f32_e32 v57, v56
	s_nop 0
	v_fma_f32 v50, -v56, v57, 1.0
	v_fmac_f32_e32 v57, v50, v57
	v_div_scale_f32 v50, vcc, 1.0, v55, 1.0
	v_mul_f32_e32 v51, v50, v57
	v_fma_f32 v52, -v56, v51, v50
	v_fmac_f32_e32 v51, v52, v57
	v_fma_f32 v50, -v56, v51, v50
	v_div_fmas_f32 v50, v50, v57, v51
	v_div_fixup_f32 v50, v50, v55, 1.0
	v_mul_f32_e32 v52, v9, v50
	v_mul_f32_e32 v48, v52, v48
	v_mul_f32_e32 v52, v10, v50
	v_mul_f32_e32 v51, v8, v50
	v_mul_f32_e32 v52, v52, v54
	v_mul_f32_e32 v50, v11, v50
	v_mul_f32_e32 v51, v51, v53
	v_mul_f32_e32 v49, v50, v49
	v_mul_f32_e32 v50, v1, v52
	v_fma_f32 v50, v0, v51, -v50
	v_mul_f32_e32 v53, v3, v49
	v_fma_f32 v53, v2, v48, -v53
	v_bfe_u32 v54, v50, 16, 1
	v_add3_u32 v50, v50, v54, s69
	v_bfe_u32 v54, v53, 16, 1
	v_lshrrev_b32_e32 v50, 16, v50
	v_add3_u32 v53, v53, v54, s69
	v_and_or_b32 v50, v53, s19, v50
	v_mul_f32_e32 v1, v1, v51
	global_store_dword v[40:41], v50, off
	v_fmac_f32_e32 v1, v0, v52
	v_mul_f32_e32 v0, v3, v48
	v_lshlrev_b32_e32 v3, 16, v47
	v_and_b32_e32 v40, 0xffff0000, v47
	v_lshlrev_b32_e32 v47, 16, v46
	v_mul_f32_e32 v41, v3, v3
	v_and_b32_e32 v46, 0xffff0000, v46
	v_mul_f32_e32 v48, v47, v47
	v_fmac_f32_e32 v41, v40, v40
	v_fmac_f32_e32 v48, v46, v46
	v_add_f32_e32 v41, v41, v48
	v_lshlrev_b32_e32 v48, 16, v45
	v_fmac_f32_e32 v0, v2, v49
	v_and_b32_e32 v45, 0xffff0000, v45
	v_mul_f32_e32 v49, v48, v48
	v_fmac_f32_e32 v49, v45, v45
	v_add_f32_e32 v41, v41, v49
	s_nop 1
	v_add_f32_dpp v41, v41, v41 quad_perm:[1,0,3,2] row_mask:0xf bank_mask:0xf
	s_nop 1
	v_add_f32_dpp v41, v41, v41 quad_perm:[2,3,0,1] row_mask:0xf bank_mask:0xf
	s_nop 1
	v_add_f32_dpp v41, v41, v41 row_half_mirror row_mask:0xf bank_mask:0xf
	s_nop 1
	v_add_f32_dpp v41, v41, v41 row_ror:8 row_mask:0xf bank_mask:0xf
	v_bfe_u32 v2, v1, 16, 1
	v_readlane_b32 s9, v41, 16
	v_readlane_b32 s8, v41, 0
	v_add3_u32 v1, v1, v2, s69
	v_mov_b32_e32 v49, s9
	v_readlane_b32 s9, v41, 48
	v_add_f32_e32 v49, s8, v49
	v_readlane_b32 s8, v41, 32
	v_mov_b32_e32 v41, s9
	v_bfe_u32 v2, v0, 16, 1
	v_add_f32_e32 v41, s8, v41
	v_add_f32_e32 v41, v49, v41
	v_fmamk_f32 v41, v41, 0x3b2aaaab, v229
	v_mul_f32_e32 v49, 0x4f800000, v41
	v_cmp_gt_f32_e32 vcc, s24, v41
	v_lshrrev_b32_e32 v1, 16, v1
	v_add3_u32 v0, v0, v2, s69
	v_cndmask_b32_e32 v41, v41, v49, vcc
	v_sqrt_f32_e32 v49, v41
	v_and_or_b32 v0, v0, s19, v1
	global_store_dword v[38:39], v0, off offset:1024
	v_add_u32_e32 v50, -1, v49
	v_fma_f32 v51, -v50, v49, v41
	v_cmp_ge_f32_e64 s[8:9], 0, v51
	v_add_u32_e32 v51, 1, v49
	s_nop 0
	v_cndmask_b32_e64 v50, v49, v50, s[8:9]
	v_fma_f32 v49, -v51, v49, v41
	v_cmp_lt_f32_e64 s[8:9], 0, v49
	s_nop 1
	v_cndmask_b32_e64 v49, v50, v51, s[8:9]
	v_mul_f32_e32 v50, 0x37800000, v49
	v_cndmask_b32_e32 v49, v49, v50, vcc
	v_cmp_class_f32_e32 vcc, v41, v230
	s_nop 1
	v_cndmask_b32_e32 v41, v49, v41, vcc
	v_div_scale_f32 v49, s[8:9], v41, v41, 1.0
	v_rcp_f32_e32 v50, v49
	s_mov_b32 s8, 0x22500000
	v_fma_f32 v0, -v49, v50, 1.0
	v_fmac_f32_e32 v50, v0, v50
	v_div_scale_f32 v0, vcc, 1.0, v41, 1.0
	v_mul_f32_e32 v1, v0, v50
	v_fma_f32 v2, -v49, v1, v0
	v_fmac_f32_e32 v1, v2, v50
	v_fma_f32 v0, -v49, v1, v0
	v_div_fmas_f32 v0, v0, v50, v1
	v_div_fixup_f32 v2, v0, v41, 1.0
	v_mul_f32_e32 v0, v2, v3
	v_mul_f32_e32 v0, v12, v0
	v_mul_f32_e32 v1, v2, v40
	v_mul_f32_e32 v1, v13, v1
	v_bfe_u32 v3, v0, 16, 1
	v_add3_u32 v0, v0, v3, s69
	v_bfe_u32 v3, v1, 16, 1
	v_lshrrev_b32_e32 v0, 16, v0
	v_add3_u32 v1, v1, v3, s69
	v_and_or_b32 v3, v1, s19, v0
	v_lshl_add_u64 v[0:1], s[10:11], 0, v[20:21]
	v_add_co_u32_e32 v0, vcc, s8, v0
	v_mul_f32_e32 v38, v2, v46
	s_nop 0
	v_addc_co_u32_e32 v1, vcc, 0, v1, vcc
	global_store_dword v[0:1], v3, off
	v_mul_f32_e32 v3, v2, v47
	v_mul_f32_e32 v3, v14, v3
	v_mul_f32_e32 v38, v15, v38
	v_bfe_u32 v39, v3, 16, 1
	v_add3_u32 v3, v3, v39, s69
	v_bfe_u32 v39, v38, 16, 1
	v_and_b32_e32 v40, 0xffff0000, v44
	v_add3_u32 v38, v38, v39, s69
	v_lshlrev_b32_e32 v39, 16, v44
	v_mul_f32_e32 v41, v40, v40
	v_fmac_f32_e32 v41, v39, v39
	s_nop 1
	v_add_f32_dpp v41, v41, v41 quad_perm:[1,0,3,2] row_mask:0xf bank_mask:0xf
	s_nop 1
	v_add_f32_dpp v41, v41, v41 quad_perm:[2,3,0,1] row_mask:0xf bank_mask:0xf
	s_nop 1
	v_add_f32_dpp v41, v41, v41 row_half_mirror row_mask:0xf bank_mask:0xf
	s_nop 1
	v_add_f32_dpp v41, v41, v41 row_ror:8 row_mask:0xf bank_mask:0xf
	v_lshrrev_b32_e32 v3, 16, v3
	v_readlane_b32 s9, v41, 16
	v_readlane_b32 s8, v41, 0
	v_and_or_b32 v3, v38, s19, v3
	v_mov_b32_e32 v44, s9
	v_readlane_b32 s9, v41, 48
	v_add_f32_e32 v44, s8, v44
	v_readlane_b32 s8, v41, 32
	v_mov_b32_e32 v41, s9
	global_store_dword v[0:1], v3, off offset:256
	v_add_f32_e32 v41, s8, v41
	v_add_f32_e32 v41, v44, v41
	v_fmamk_f32 v41, v41, 0x3c000000, v229
	v_mul_f32_e32 v44, 0x4f800000, v41
	v_cmp_gt_f32_e32 vcc, s24, v41
	v_mul_f32_e32 v3, v2, v48
	v_mul_f32_e32 v2, v2, v45
	v_cndmask_b32_e32 v41, v41, v44, vcc
	v_sqrt_f32_e32 v44, v41
	v_mul_f32_e32 v3, v16, v3
	v_mul_f32_e32 v2, v17, v2
	v_bfe_u32 v38, v3, 16, 1
	v_add_u32_e32 v45, -1, v44
	v_fma_f32 v46, -v45, v44, v41
	v_cmp_ge_f32_e64 s[8:9], 0, v46
	v_add_u32_e32 v46, 1, v44
	v_add3_u32 v3, v3, v38, s69
	v_cndmask_b32_e64 v45, v44, v45, s[8:9]
	v_fma_f32 v44, -v46, v44, v41
	v_cmp_lt_f32_e64 s[8:9], 0, v44
	v_bfe_u32 v38, v2, 16, 1
	v_lshrrev_b32_e32 v3, 16, v3
	v_cndmask_b32_e64 v44, v45, v46, s[8:9]
	v_mul_f32_e32 v45, 0x37800000, v44
	v_cndmask_b32_e32 v44, v44, v45, vcc
	v_cmp_class_f32_e32 vcc, v41, v230
	v_add3_u32 v2, v2, v38, s69
	v_and_or_b32 v2, v2, s19, v3
	v_cndmask_b32_e32 v41, v44, v41, vcc
	v_div_scale_f32 v44, s[8:9], v41, v41, 1.0
	v_rcp_f32_e32 v45, v44
	global_store_dword v[0:1], v2, off offset:512
	v_fma_f32 v2, -v44, v45, 1.0
	v_fmac_f32_e32 v45, v2, v45
	v_div_scale_f32 v2, vcc, 1.0, v41, 1.0
	v_mul_f32_e32 v3, v2, v45
	v_fma_f32 v38, -v44, v3, v2
	v_fmac_f32_e32 v3, v38, v45
	v_fma_f32 v2, -v44, v3, v2
	v_div_fmas_f32 v2, v2, v45, v3
	v_div_fixup_f32 v2, v2, v41, 1.0
	v_mul_f32_e32 v3, v2, v39
	v_mul_f32_e32 v3, v18, v3
	v_mul_f32_e32 v2, v2, v40
	v_mul_f32_e32 v2, v19, v2
	v_bfe_u32 v38, v3, 16, 1
	v_add3_u32 v3, v3, v38, s69
	v_bfe_u32 v38, v2, 16, 1
	v_lshrrev_b32_e32 v3, 16, v3
	v_add3_u32 v2, v2, v38, s69
	v_and_or_b32 v2, v2, s19, v3
	global_store_dword v[0:1], v2, off offset:768
	s_and_saveexec_b64 s[8:9], s[16:17]
	s_cbranch_execz .LBB0_329
	v_pk_mul_f32 v[0:1], v[34:35], v[36:37] op_sel:[0,1] op_sel_hi:[1,0]
	s_nop 0
	v_pk_fma_f32 v[0:1], v[34:35], v[36:37], v[0:1] op_sel:[1,0,0] op_sel_hi:[0,1,1] neg_lo:[0,0,1] neg_hi:[0,0,1]
	v_bfe_u32 v1, v0, 16, 1
	v_add3_u32 v0, v0, v1, s69
	global_store_short_d16_hi v[32:33], v0, off
	v_mul_f32_e32 v0, v35, v37
	v_pk_fma_f32 v[0:1], v[34:35], v[36:37], v[0:1] op_sel_hi:[1,1,0]
	s_nop 0
	v_bfe_u32 v1, v0, 16, 1
	v_add3_u32 v2, v0, v1, s69
	v_add_co_u32_e32 v0, vcc, 0x19401000, v30
	s_nop 1
	v_addc_co_u32_e32 v1, vcc, 0, v31, vcc
	global_store_short_d16_hi v[0:1], v2, off offset:2080
	s_branch .LBB0_329
